# M2: half of the workgroups run the PEER table quantisation stream before their GEMM tile instead of after it
# baseline (speedup 1.0000x reference)
; #define TIDX512 launder_i((int)threadIdx.x)
; __device__ __forceinline__ int vblk() { return (int)blockIdx.x * 2 + half_id(); }
; __device__ __forceinline__ int vgrid() { return (int)gridDim.x * 2; }
; __device__ void phaseM2(const Params& p, char* lds) {
;     const int tid_ = TIDX512; const int lane = tid_ & 63, wave = tid_ >> 6;
;     const int wr = wave >> 2, wc = wave & 3, r = lane & 15, q = lane >> 4;
;     const bf16_t* M = (const bf16_t*)(p.ws + OFF_M);
;     const float* mod = (const float*)(p.ws + OFF_MOD);
;     TileIter tit(4, lds);
;     int bm, bn;
;     while (tit.next(bm, bn)) {
;         const int m0 = bm * 256, n0 = bn * 256;
;         f32x4 acc[8][4];
;         zero_acc(acc);
;         gemm_core(acc, M, DM, (const bf16_t*)(p.ws + OFF_WO), DM, DM, m0, n0, lds);
;     ...
;     {
;         const int tid_ = TIDX; const int lane = tid_ & 63, wave = tid_ >> 6;
;         unsigned char* tq = (unsigned char*)(p.ws + OFF_UB);
;         float* tsc = (float*)(p.ws + OFF_UB + 33554432);
;         for (int row = vblk() * 4 + wave; row < 32768; row += vgrid() * 4) {
;             const bool isv = row >= 16384;
;             const float* srcp = (isv ? p.peer_v : p.peer_u) + (size_t)(row & 16383) * DM + lane * 16;
.LBB0_774:
	s_or_b64 exec, exec, s[4:5]
	s_mov_b64 s[8:9], s[80:81]
	s_waitcnt lgkmcnt(0)
	v_mov_b32_e32 v0, v158
	s_barrier
	v_readlane_b32 s98, v222, 0
	s_bfe_u32 s98, s98, 0x10003
	s_cmp_eq_u32 s98, 0
	s_cbranch_scc1 .Lm2_gemm
	s_load_dwordx2 s[6:7], s[8:9], 0xd8
	s_waitcnt lgkmcnt(0)
	s_branch .Lm2_quant
.Lm2_gemm:
	v_mov_b32_e32 v0, v158
	s_load_dwordx2 s[6:7], s[8:9], 0xd8
	v_bfe_u32 v1, v0, 6, 2
	v_and_b32_e32 v160, 15, v0
	v_bfe_u32 v2, v0, 4, 2
	v_ashrrev_i32_e32 v0, 1, v0
	s_waitcnt lgkmcnt(0)
	s_add_u32 s4, s6, 0x3c00000
	s_addc_u32 s5, s7, 0
	v_and_b32_e32 v161, 0xffffff80, v0
	v_lshlrev_b32_e32 v0, 2, v2
	s_add_u32 s10, s6, 0x15c0000
	v_lshl_or_b32 v162, v1, 6, v0
	v_lshlrev_b32_e32 v0, 7, v1
	v_or_b32_e32 v1, v161, v160
	s_movk_i32 s0, 0x210
	s_addc_u32 s11, s7, 0
	v_lshl_or_b32 v0, v2, 3, v0
	v_mul_lo_u32 v1, v1, s0
	s_add_u32 s1, s6, 0xbd00000
	s_addc_u32 s2, s7, 0
	v_mov_b32_e32 v153, 0
	s_movk_i32 s3, 0x3f0
	s_movk_i32 s42, 0xf000
	s_mov_b64 s[12:13], 0x4000
	s_movk_i32 s43, 0x400
	s_mov_b64 s[14:15], 0x8000
	s_mov_b64 s[16:17], 0xc000
	s_mov_b32 s44, 0x10000
	s_mov_b64 s[18:19], 0x3c00080
	s_mov_b64 s[20:21], 0x15c0080
	s_mov_b64 s[22:23], 0x3c04080
	s_mov_b64 s[24:25], 0x15c4080
	s_mov_b64 s[26:27], 0x3c08080
	s_mov_b64 s[28:29], 0x15c8080
	s_mov_b64 s[30:31], 0x3c0c080
	s_mov_b64 s[34:35], 0x15cc080
	s_mov_b64 s[36:37], 0x6000
	v_add_u32_e32 v163, v0, v1
	s_mov_b32 s45, s50
	s_branch .LBB0_777

; __device__ void phaseM2(const Params& p, char* lds) {
;     ...
;         __syncthreads();
;         epi_store(lds, (bf16_t*)(p.ws + OFF_X1B), DM, m0, n0, DM);
;         __syncthreads();
;     }
;     {
.LBB0_790:
	s_cmp_eq_u32 s98, 2
	s_cbranch_scc1 .Lm2_done

; __device__ __forceinline__ unsigned xb_add(unsigned* p, unsigned v) { return __hip_atomic_fetch_add(p, v, __ATOMIC_RELAXED, __HIP_MEMORY_SCOPE_AGENT); }
; __device__ __forceinline__ void xcd_barrier(const XcdBarrier& b) {
;     asm volatile("s_waitcnt vmcnt(0)" ::: "memory");
;     __syncthreads();
;     if (threadIdx.x == 0) {
;         unsigned* bar = b.bar;
;         __builtin_amdgcn_s_waitcnt(0);
;         unsigned nloc = b.st[0], nx = b.st[1];
;         if (nloc == 0u) { unsigned bal; xcd_barrier_complete(bar, b.x, nloc, nx, bal); b.st[0] = nloc; b.st[1] = nx; b.st[3] = bal; }
;         const unsigned old = xb_add(&bar[XB_XSUB(b.x)], 1u);
;         const unsigned gen = old / nloc;
;         if (old + 1u == (gen + 1u) * nloc) {
;             __builtin_amdgcn_fence(__ATOMIC_RELEASE, "agent");
;             asm volatile("s_waitcnt vmcnt(0)" ::: "memory");
.LBB0_801:
	s_or_b64 exec, exec, s[10:11]
	s_cmp_eq_u32 s98, 1
	s_cbranch_scc0 .Lm2_done
	s_mov_b32 s98, 2
	s_branch .Lm2_gemm
.Lm2_done:
	v_readlane_b32 s28, v222, 5
	s_waitcnt vmcnt(0)
	s_barrier
	s_mov_b64 s[4:5], exec
	v_readlane_b32 s0, v222, 1
	v_readlane_b32 s1, v222, 2
	s_and_b64 s[0:1], s[4:5], s[0:1]
	s_mov_b64 exec, s[0:1]
	s_cbranch_execz .LBB0_852
	v_mov_b32_e32 v0, 0x24000
	s_waitcnt vmcnt(0) expcnt(0) lgkmcnt(0)
	ds_read_b32 v2, v0
	v_mov_b32_e32 v0, 0x24004
	ds_read_b32 v0, v0
	s_waitcnt lgkmcnt(1)
	v_cmp_ne_u32_e32 vcc, 0, v2
	s_cbranch_vccnz .LBB0_816
	s_add_u32 s8, s78, 0x1000
	s_addc_u32 s9, s79, 0
	s_add_u32 s10, s78, 0x1100
	s_addc_u32 s11, s79, 0
	s_add_u32 s12, s78, 0x1200
	s_addc_u32 s13, s79, 0
	s_mul_i32 s0, s73, s76
	s_add_u32 s14, s78, 0x1300
	s_mul_i32 s0, s0, s72
	s_addc_u32 s15, s79, 0
	s_mov_b32 s1, 1
	v_mov_b32_e32 v16, 0
	s_branch .LBB0_805

; __global__ void __launch_bounds__(BLOCK_THREADS, 2) mega(Params p_unused) {
;     __shared__ __attribute__((aligned(16))) char lds[LDS_BYTES];
	.amdhsa_kernel _Z4mega6Params
		.amdhsa_group_segment_fixed_size 147520
		.amdhsa_private_segment_fixed_size 0
		.amdhsa_kernarg_size 480
		.amdhsa_user_sgpr_count 2
		.amdhsa_user_sgpr_dispatch_ptr 0
		.amdhsa_user_sgpr_queue_ptr 0
		.amdhsa_user_sgpr_kernarg_segment_ptr 1
		.amdhsa_user_sgpr_dispatch_id 0
		.amdhsa_user_sgpr_kernarg_preload_length 0
		.amdhsa_user_sgpr_kernarg_preload_offset 0
		.amdhsa_user_sgpr_private_segment_size 0
		.amdhsa_uses_dynamic_stack 0
		.amdhsa_enable_private_segment 0
		.amdhsa_system_sgpr_workgroup_id_x 1
		.amdhsa_system_sgpr_workgroup_id_y 0
		.amdhsa_system_sgpr_workgroup_id_z 0
		.amdhsa_system_sgpr_workgroup_info 0
		.amdhsa_system_vgpr_workitem_id 2
		.amdhsa_next_free_vgpr 256
		.amdhsa_next_free_sgpr 99
		.amdhsa_accum_offset 256
		.amdhsa_reserve_vcc 1
		.amdhsa_float_round_mode_32 0
		.amdhsa_float_round_mode_16_64 0
		.amdhsa_float_denorm_mode_32 3
		.amdhsa_float_denorm_mode_16_64 3
		.amdhsa_dx10_clamp 1
		.amdhsa_ieee_mode 1
		.amdhsa_fp16_overflow 0
		.amdhsa_tg_split 0
		.amdhsa_exception_fp_ieee_invalid_op 0
		.amdhsa_exception_fp_denorm_src 0
		.amdhsa_exception_fp_ieee_div_zero 0
		.amdhsa_exception_fp_ieee_overflow 0
		.amdhsa_exception_fp_ieee_underflow 0
		.amdhsa_exception_fp_ieee_inexact 0
		.amdhsa_exception_int_div_zero 0
	.end_amdhsa_kernel

; __global__ void __launch_bounds__(BLOCK_THREADS, 2) mega(Params p_unused) {
;     __shared__ __attribute__((aligned(16))) char lds[LDS_BYTES];
amdhsa.kernels:
  - .agpr_count:     0
    .args:
      - .offset:         0
        .size:           224
        .value_kind:     by_value
      - .offset:         224
        .size:           4
        .value_kind:     hidden_block_count_x
      - .offset:         228
        .size:           4
        .value_kind:     hidden_block_count_y
      - .offset:         232
        .size:           4
        .value_kind:     hidden_block_count_z
      - .offset:         236
        .size:           2
        .value_kind:     hidden_group_size_x
      - .offset:         238
        .size:           2
        .value_kind:     hidden_group_size_y
      - .offset:         240
        .size:           2
        .value_kind:     hidden_group_size_z
      - .offset:         242
        .size:           2
        .value_kind:     hidden_remainder_x
      - .offset:         244
        .size:           2
        .value_kind:     hidden_remainder_y
      - .offset:         246
        .size:           2
        .value_kind:     hidden_remainder_z
      - .offset:         264
        .size:           8
        .value_kind:     hidden_global_offset_x
      - .offset:         272
        .size:           8
        .value_kind:     hidden_global_offset_y
      - .offset:         280
        .size:           8
        .value_kind:     hidden_global_offset_z
      - .offset:         288
        .size:           2
        .value_kind:     hidden_grid_dims
      - .offset:         312
        .size:           8
        .value_kind:     hidden_multigrid_sync_arg
    .group_segment_fixed_size: 147520
    .kernarg_segment_align: 8
    .kernarg_segment_size: 480
    .language:       OpenCL C
    .language_version:
      - 2
      - 0
    .max_flat_workgroup_size: 512
    .name:           _Z4mega6Params
    .private_segment_fixed_size: 0
    .sgpr_count:     105
    .sgpr_spill_count: 19
    .symbol:         _Z4mega6Params.kd
    .uniform_work_group_size: 1
    .uses_dynamic_stack: false
    .vgpr_count:     256
    .vgpr_spill_count: 0
    .wavefront_size: 64
